# passC walk + flat->global + barrier poll loops without s_sleep
# baseline (speedup 1.0000x reference)
; DI unsigned xb_ld(unsigned* p)              { return __hip_atomic_load(p, __ATOMIC_RELAXED, __HIP_MEMORY_SCOPE_AGENT); }
; DI void xcd_barrier_complete(unsigned* bar, unsigned x, unsigned& nloc, unsigned& nx) {
;     ...
;     for (;;) {
;         sum = 0u; cnt = 0u; mine = 0u;
; #pragma unroll
;         for (unsigned j = 0; j < 16; ++j) { const unsigned c = xb_ld(&bar[XB_XCNT(j)]); sum += c; cnt += (c > 0u) ? 1u : 0u; mine = (j == x) ? c : mine; }
;         if (sum == G) break;
;         __builtin_amdgcn_s_sleep(1);
;         if ((++sp & 255u) == 0u) { if (xb_ld(&bar[XB_TMO])) break; if (sp > XB_SPIN_CAP) { atomicAdd(&bar[XB_TMO], 1u); break; } }
;     }
;     nloc = mine > 0u ? mine : 1u; nx = cnt > 0u ? cnt : 1u;
.LBB0_500:
	global_load_dword v16, v1, s[80:81] offset:1024 sc1
	global_load_dword v0, v1, s[80:81] offset:1280 sc1
	s_waitcnt lgkmcnt(0)
	global_load_dword v2, v1, s[80:81] offset:1536 sc1
	global_load_dword v3, v1, s[80:81] offset:1792 sc1
	global_load_dword v4, v1, s[80:81] offset:2048 sc1
	global_load_dword v5, v1, s[80:81] offset:2304 sc1
	global_load_dword v6, v1, s[80:81] offset:2560 sc1
	global_load_dword v7, v1, s[80:81] offset:2816 sc1
	global_load_dword v8, v1, s[80:81] offset:3072 sc1
	global_load_dword v9, v1, s[80:81] offset:3328 sc1
	global_load_dword v10, v1, s[80:81] offset:3584 sc1
	global_load_dword v11, v1, s[80:81] offset:3840 sc1
	global_load_dword v12, v1, s[12:13] sc1
	global_load_dword v13, v1, s[16:17] sc1
	global_load_dword v14, v1, s[18:19] sc1
	global_load_dword v15, v1, s[20:21] sc1
	s_mov_b64 s[2:3], -1
	s_mov_b64 s[6:7], -1
	s_waitcnt vmcnt(14)
	v_add_u32_e32 v17, v0, v16
	s_waitcnt vmcnt(13)
	v_add_u32_e32 v17, v17, v2
	s_waitcnt vmcnt(12)
	v_add_u32_e32 v17, v17, v3
	s_waitcnt vmcnt(11)
	v_add_u32_e32 v17, v17, v4
	s_waitcnt vmcnt(10)
	v_add_u32_e32 v17, v17, v5
	s_waitcnt vmcnt(9)
	v_add_u32_e32 v17, v17, v6
	s_waitcnt vmcnt(8)
	v_add_u32_e32 v17, v17, v7
	s_waitcnt vmcnt(7)
	v_add_u32_e32 v17, v17, v8
	s_waitcnt vmcnt(6)
	v_add_u32_e32 v17, v17, v9
	s_waitcnt vmcnt(5)
	v_add_u32_e32 v17, v17, v10
	s_waitcnt vmcnt(4)
	v_add_u32_e32 v17, v17, v11
	s_waitcnt vmcnt(3)
	v_add_u32_e32 v17, v17, v12
	s_waitcnt vmcnt(2)
	v_add_u32_e32 v17, v17, v13
	s_waitcnt vmcnt(1)
	v_add_u32_e32 v17, v17, v14
	s_waitcnt vmcnt(0)
	v_add_u32_e32 v17, v17, v15
	v_cmp_eq_u32_e32 vcc, s89, v17
	s_cbranch_vccnz .LBB0_499
	s_and_b32 s2, s8, 0xff
	s_cmp_eq_u32 s2, 0
	s_mov_b64 s[2:3], -1
	s_mov_b64 s[14:15], -1
	s_nop 0
	s_cbranch_scc1 .LBB0_504
	s_and_b64 vcc, exec, s[14:15]
	s_cbranch_vccz .LBB0_499

; DI unsigned xb_ld(unsigned* p)              { return __hip_atomic_load(p, __ATOMIC_RELAXED, __HIP_MEMORY_SCOPE_AGENT); }
; DI unsigned xb_add(unsigned* p, unsigned v) { return __hip_atomic_fetch_add(p, v, __ATOMIC_RELAXED, __HIP_MEMORY_SCOPE_AGENT); }
; #define XB_SPIN(cond, bar) do { unsigned _sp = 0; while (cond) { __builtin_amdgcn_s_sleep(1); \
;     if ((++_sp & 255u) == 0u) { if (xb_ld(&(bar)[XB_TMO])) break; if (_sp > XB_SPIN_CAP) { atomicAdd(&(bar)[XB_TMO], 1u); break; } } } } while (0)
; DI void xcd_barrier(const XcdBarrier& b) {
;     ...
;             const unsigned tg = og / nx;
;             if (og + 1u == (tg + 1u) * nx) xb_add(&bar[XB_TOPGEN], 1u);
;             else XB_SPIN(xb_ld(&bar[XB_TOPGEN]) == tg, bar);
;             __builtin_amdgcn_fence(__ATOMIC_ACQUIRE, "agent");
;             xb_add(&bar[XB_XGEN(b.x)], 1u);
;             asm volatile("s_waitcnt vmcnt(0)" ::: "memory");
;         } else {
;             XB_SPIN(xb_ld(&bar[XB_XGEN(b.x)]) == gen, bar);
;             __builtin_amdgcn_fence(__ATOMIC_ACQUIRE, "agent");
.LBB0_520:
	s_and_b32 s12, s8, 0xff
	s_mov_b64 s[18:19], -1
	s_cmp_lg_u32 s12, 0
	s_mov_b64 s[22:23], -1
	s_nop 0
	s_cbranch_scc0 .LBB0_523
	s_and_b64 vcc, exec, s[22:23]
	s_cbranch_vccz .LBB0_519
